# RES epilogue for split-K context tiles: 32 gate*acc partial stores issued back to back (no per-block vmcnt(0) / LDS pointer re-read)
# speedup vs baseline: 1.0002x; 1.0002x over previous
.LBB0_906:
	s_andn2_b64 vcc, exec, s[8:9]
	s_cbranch_vccnz .LBB0_1036
	s_cmp_lt_i32 s66, 64
	s_cselect_b64 s[2:3], -1, 0
	s_cmp_gt_i32 s66, 63
	s_movk_i32 s4, 0x68
	s_cselect_b32 s4, 0x70, s4
	s_movk_i32 s5, 0x48
	s_movk_i32 s7, 0x58
	v_readlane_b32 s8, v253, 34
	s_cselect_b32 s5, 0x50, s5
	s_cselect_b32 s6, 0xffffc000, 0
	s_cselect_b32 s7, 0x60, s7
	s_add_i32 s4, s8, s4
	v_mov_b32_e32 v0, s4
	ds_read_b64 v[130:131], v0
	s_add_i32 s4, s8, s5
	v_ashrrev_i32_e32 v163, 31, v162
	v_mov_b32_e32 v0, s4
	s_add_i32 s4, s8, s7
	v_mov_b32_e32 v132, s4
	s_waitcnt lgkmcnt(0)
	v_lshl_add_u64 v[130:131], v[162:163], 2, v[130:131]
	ds_read_b64 v[166:167], v0
	ds_read_b64 v[164:165], v132
	global_load_dwordx4 v[142:145], v[130:131], off
	global_load_dwordx4 v[138:141], v[130:131], off offset:64
	global_load_dwordx4 v[134:137], v[130:131], off offset:512
	s_nop 0
	global_load_dwordx4 v[130:133], v[130:131], off offset:576
	v_add_u32_e32 v168, s6, v160
	v_ashrrev_i32_e32 v169, 31, v168
	v_lshlrev_b64 v[146:147], 10, v[168:169]
	v_lshl_add_u64 v[170:171], v[146:147], 0, v[162:163]
	v_lshlrev_b64 v[146:147], 2, v[170:171]
	s_waitcnt lgkmcnt(0)
	v_lshl_add_u64 v[172:173], v[166:167], 0, v[146:147]
	v_lshl_add_u64 v[174:175], v[164:165], 0, v[146:147]
	s_and_b64 vcc, exec, s[2:3]
	s_cbranch_vccz .Lres_isc_fast
	s_mov_b64 s[4:5], -1
	s_and_b64 vcc, exec, s[2:3]
	s_cbranch_vccz .LBB0_909
	global_load_dwordx4 v[146:149], v[172:173], off
	s_mov_b64 s[4:5], 0
	s_waitcnt vmcnt(0)
	v_pk_fma_f32 v[148:149], v[128:129], v[144:145], v[148:149]
	v_pk_fma_f32 v[146:147], v[126:127], v[142:143], v[146:147]
	global_store_dwordx4 v[174:175], v[146:149], off

.Lres_isc_fast:
	v_readlane_b32 s6, v253, 29
	v_mov_b32_e32 v176, s6
	ds_read_b64 v[176:177], v176
	s_ashr_i32 s4, s26, 1
	s_ashr_i32 s5, s4, 31
	s_lshl_b64 s[4:5], s[4:5], 20
	s_waitcnt lgkmcnt(0)
	v_lshl_add_u64 v[176:177], v[176:177], 0, s[4:5]
	v_lshl_add_u64 v[176:177], v[170:171], 2, v[176:177]
	s_mov_b64 s[4:5], 0x10000
	s_mov_b64 s[6:7], 0x50000
	s_waitcnt vmcnt(0)
	v_pk_mul_f32 v[206:207], v[126:127], v[142:143]
	v_pk_mul_f32 v[208:209], v[128:129], v[144:145]
	v_pk_mul_f32 v[210:211], v[118:119], v[138:139]
	v_pk_mul_f32 v[212:213], v[120:121], v[140:141]
	v_pk_mul_f32 v[214:215], v[122:123], v[134:135]
	v_pk_mul_f32 v[216:217], v[124:125], v[136:137]
	v_pk_mul_f32 v[218:219], v[114:115], v[130:131]
	v_pk_mul_f32 v[220:221], v[116:117], v[132:133]
	global_store_dwordx4 v[176:177], v[206:209], off
	global_store_dwordx4 v[176:177], v[210:213], off offset:64
	global_store_dwordx4 v[176:177], v[214:217], off offset:512
	global_store_dwordx4 v[176:177], v[218:221], off offset:576
	s_nop 0
	v_lshl_add_u64 v[176:177], v[176:177], 0, s[4:5]
	v_pk_mul_f32 v[222:223], v[110:111], v[142:143]
	v_pk_mul_f32 v[224:225], v[112:113], v[144:145]
	v_pk_mul_f32 v[226:227], v[102:103], v[138:139]
	v_pk_mul_f32 v[228:229], v[104:105], v[140:141]
	v_pk_mul_f32 v[236:237], v[106:107], v[134:135]
	v_pk_mul_f32 v[238:239], v[108:109], v[136:137]
	v_pk_mul_f32 v[240:241], v[98:99], v[130:131]
	v_pk_mul_f32 v[242:243], v[100:101], v[132:133]
	global_store_dwordx4 v[176:177], v[222:225], off
	global_store_dwordx4 v[176:177], v[226:229], off offset:64
	global_store_dwordx4 v[176:177], v[236:239], off offset:512
	global_store_dwordx4 v[176:177], v[240:243], off offset:576
	s_nop 0
	v_lshl_add_u64 v[176:177], v[176:177], 0, s[4:5]
	v_pk_mul_f32 v[244:245], v[94:95], v[142:143]
	v_pk_mul_f32 v[246:247], v[96:97], v[144:145]
	v_pk_mul_f32 v[146:147], v[86:87], v[138:139]
	v_pk_mul_f32 v[148:149], v[88:89], v[140:141]
	v_pk_mul_f32 v[168:169], v[90:91], v[134:135]
	v_pk_mul_f32 v[170:171], v[92:93], v[136:137]
	v_pk_mul_f32 v[164:165], v[82:83], v[130:131]
	v_pk_mul_f32 v[166:167], v[84:85], v[132:133]
	global_store_dwordx4 v[176:177], v[244:247], off
	global_store_dwordx4 v[176:177], v[146:149], off offset:64
	global_store_dwordx4 v[176:177], v[168:171], off offset:512
	global_store_dwordx4 v[176:177], v[164:167], off offset:576
	s_nop 0
	v_lshl_add_u64 v[176:177], v[176:177], 0, s[4:5]
	v_pk_mul_f32 v[206:207], v[78:79], v[142:143]
	v_pk_mul_f32 v[208:209], v[80:81], v[144:145]
	v_pk_mul_f32 v[210:211], v[70:71], v[138:139]
	v_pk_mul_f32 v[212:213], v[72:73], v[140:141]
	v_pk_mul_f32 v[214:215], v[74:75], v[134:135]
	v_pk_mul_f32 v[216:217], v[76:77], v[136:137]
	v_pk_mul_f32 v[218:219], v[66:67], v[130:131]
	v_pk_mul_f32 v[220:221], v[68:69], v[132:133]
	global_store_dwordx4 v[176:177], v[206:209], off
	global_store_dwordx4 v[176:177], v[210:213], off offset:64
	global_store_dwordx4 v[176:177], v[214:217], off offset:512
	global_store_dwordx4 v[176:177], v[218:221], off offset:576
	s_nop 0
	v_lshl_add_u64 v[176:177], v[176:177], 0, s[6:7]
	v_pk_mul_f32 v[222:223], v[62:63], v[142:143]
	v_pk_mul_f32 v[224:225], v[64:65], v[144:145]
	v_pk_mul_f32 v[226:227], v[54:55], v[138:139]
	v_pk_mul_f32 v[228:229], v[56:57], v[140:141]
	v_pk_mul_f32 v[236:237], v[58:59], v[134:135]
	v_pk_mul_f32 v[238:239], v[60:61], v[136:137]
	v_pk_mul_f32 v[240:241], v[50:51], v[130:131]
	v_pk_mul_f32 v[242:243], v[52:53], v[132:133]
	global_store_dwordx4 v[176:177], v[222:225], off
	global_store_dwordx4 v[176:177], v[226:229], off offset:64
	global_store_dwordx4 v[176:177], v[236:239], off offset:512
	global_store_dwordx4 v[176:177], v[240:243], off offset:576
	s_nop 0
	v_lshl_add_u64 v[176:177], v[176:177], 0, s[4:5]
	v_pk_mul_f32 v[244:245], v[46:47], v[142:143]
	v_pk_mul_f32 v[246:247], v[48:49], v[144:145]
	v_pk_mul_f32 v[146:147], v[38:39], v[138:139]
	v_pk_mul_f32 v[148:149], v[40:41], v[140:141]
	v_pk_mul_f32 v[168:169], v[42:43], v[134:135]
	v_pk_mul_f32 v[170:171], v[44:45], v[136:137]
	v_pk_mul_f32 v[164:165], v[34:35], v[130:131]
	v_pk_mul_f32 v[166:167], v[36:37], v[132:133]
	global_store_dwordx4 v[176:177], v[244:247], off
	global_store_dwordx4 v[176:177], v[146:149], off offset:64
	global_store_dwordx4 v[176:177], v[168:171], off offset:512
	global_store_dwordx4 v[176:177], v[164:167], off offset:576
	s_nop 0
	v_lshl_add_u64 v[176:177], v[176:177], 0, s[4:5]
	v_pk_mul_f32 v[206:207], v[30:31], v[142:143]
	v_pk_mul_f32 v[208:209], v[32:33], v[144:145]
	v_pk_mul_f32 v[210:211], v[22:23], v[138:139]
	v_pk_mul_f32 v[212:213], v[24:25], v[140:141]
	v_pk_mul_f32 v[214:215], v[26:27], v[134:135]
	v_pk_mul_f32 v[216:217], v[28:29], v[136:137]
	v_pk_mul_f32 v[218:219], v[18:19], v[130:131]
	v_pk_mul_f32 v[220:221], v[20:21], v[132:133]
	global_store_dwordx4 v[176:177], v[206:209], off
	global_store_dwordx4 v[176:177], v[210:213], off offset:64
	global_store_dwordx4 v[176:177], v[214:217], off offset:512
	global_store_dwordx4 v[176:177], v[218:221], off offset:576
	s_nop 0
	v_lshl_add_u64 v[176:177], v[176:177], 0, s[4:5]
	v_pk_mul_f32 v[222:223], v[14:15], v[142:143]
	v_pk_mul_f32 v[224:225], v[16:17], v[144:145]
	v_pk_mul_f32 v[226:227], v[6:7], v[138:139]
	v_pk_mul_f32 v[228:229], v[8:9], v[140:141]
	v_pk_mul_f32 v[236:237], v[10:11], v[134:135]
	v_pk_mul_f32 v[238:239], v[12:13], v[136:137]
	v_pk_mul_f32 v[240:241], v[2:3], v[130:131]
	v_pk_mul_f32 v[242:243], v[4:5], v[132:133]
	global_store_dwordx4 v[176:177], v[222:225], off
	global_store_dwordx4 v[176:177], v[226:229], off offset:64
	global_store_dwordx4 v[176:177], v[236:239], off offset:512
	global_store_dwordx4 v[176:177], v[240:243], off offset:576
	s_branch .LBB0_816
